# v36 with 4 B never-executed padding after the scan body: code after it back at the baseline byte phase (placement sensitivity check of the later GEMM loops)
# speedup vs baseline: 1.0119x; 1.0119x over previous
; #define LAS __attribute__((address_space(3)))
; __device__ __forceinline__ float row16_sum(float v) { v += dpp_f<0xB1>(v); v += dpp_f<0x4E>(v); v += dpp_f<0x141>(v); v += dpp_f<0x140>(v); return v; }
; __device__ __forceinline__ void rwkv_scan_unit(LAS unsigned char* lds, const float* Wd, const float* V, const bf16_t* RKKB, float* Yraw, int p, int rg, int tid) {
;     ...
;     for (int c = 0; c < NCH; ++c) {
;         if (wave >= 4) { if (c + 2 < NCH) scan_load_chunk(lds + ((c + 2) % 3) * SCAN_SLOT_B, Wd, V, RKKB, p, rg, (c + 2) * SCAN_CH, tid - 256); }
;         else {
;             LAS const unsigned char* sl = lds + (c % 3) * SCAN_SLOT_B + kq * 16;
;             LAS const unsigned char* vl = lds + (c % 3) * SCAN_SLOT_B + 1280 + rl * 4;
;             float* yo = Yraw + ((size_t)p * SEQ + c * SCAN_CH + kq) * 64 + rg * 16 + rl;
;             f32x4 w = *(LAS const f32x4*)(sl), b = *(LAS const f32x4*)(sl + 256), k = *(LAS const f32x4*)(sl + 512), kk = *(LAS const f32x4*)(sl + 768), r = *(LAS const f32x4*)(sl + 1024);
;             float v = *(LAS const float*)(vl); float yp[16];
; #pragma unroll
;             for (int st = 0; st < SCAN_CH; ++st) {
;                 f32x4 wn = w, bn = b, kn = k, kkn = kk, rn = r; float vn = v;
;                 if (st + 1 < SCAN_CH) { const int o = (st + 1) * SCAN_STEP_B;
;                     wn = *(LAS const f32x4*)(sl + o); bn = *(LAS const f32x4*)(sl + o + 256); kn = *(LAS const f32x4*)(sl + o + 512); kkn = *(LAS const f32x4*)(sl + o + 768); rn = *(LAS const f32x4*)(sl + o + 1024);
;                     vn = *(LAS const float*)(vl + o); }
;                 float sa = (S[0] * kk[0] + S[1] * kk[1]) + (S[2] * kk[2] + S[3] * kk[3]);
;                 const f32x4 kvt = k * v;
;                 sa = -row16_sum(sa);
;                 S = S * w + (b * sa + kvt);
;                 yp[st & 15] = (S[0] * r[0] + S[1] * r[1]) + (S[2] * r[2] + S[3] * r[3]);
;                 if ((st & 15) == 15) yo[(size_t)(st - 15) * 64] = tr16_sum(yp, kq);
;                 w = wn; b = bn; k = kn; kk = kkn; r = rn; v = vn;
;             }
.Lscan_top:
	s_mul_i32 s18, s22, 0xab
	s_bfe_u32 s18, s18, 0x70009
	s_mul_i32 s18, s18, 3
	s_sub_i32 s18, s22, s18
	s_and_b32 s18, s18, 0xff
	s_mul_i32 s18, s18, 0xa800
	s_add_i32 s19, s18, 0xa800
	s_cmp_eq_u32 s19, 0x1f800
	s_cselect_b32 s19, 0, s19
	v_add_u32_e32 v84, s18, v71
	v_add_u32_e32 v83, s18, v72
	v_add_u32_e32 v86, s19, v71
	v_add_u32_e32 v85, s19, v72
	v_lshl_add_u64 v[62:63], v[60:61], 0, s[14:15]
	s_mov_b64 s[20:21], 0x16100000
	v_lshl_add_u64 v[88:89], v[62:63], 0, s[20:21]
	s_mov_b64 s[20:21], 0x16101000
	v_lshl_add_u64 v[90:91], v[62:63], 0, s[20:21]
	s_lshr_b32 s20, s18, 15
	s_lshl_b32 s20, s20, 11
	s_add_i32 s20, s20, 0x1f800
	v_lshl_add_u32 v96, v72, 5, s20
	s_lshr_b32 s21, s19, 15
	s_lshl_b32 s21, s21, 11
	s_add_i32 s21, s21, 0x1f800
	v_lshl_add_u32 v97, v72, 5, s21
	s_waitcnt lgkmcnt(5)
	v_pk_mul_f32 v[10:11], v[2:3], v[132:133]
	v_pk_fma_f32 v[10:11], v[4:5], v[134:135], v[10:11]
	v_pk_mul_f32 v[6:7], v[128:129], v[116:117] op_sel_hi:[1,0]
	v_add_f32_e32 v12, v10, v11
	v_pk_mul_f32 v[8:9], v[130:131], v[116:117] op_sel_hi:[1,0]
	v_pk_fma_f32 v[6:7], v[2:3], v[120:121], v[6:7]
	v_add_f32_dpp v12, v12, v12 quad_perm:[1,0,3,2] row_mask:0xf bank_mask:0xf bound_ctrl:1
	v_pk_fma_f32 v[8:9], v[4:5], v[122:123], v[8:9]
	ds_read_b128 v[180:183], v84 offset:3456
	v_add_f32_dpp v12, v12, v12 quad_perm:[2,3,0,1] row_mask:0xf bank_mask:0xf bound_ctrl:1
	ds_read_b128 v[168:171], v84 offset:2688
	ds_read_b128 v[176:179], v84 offset:3200
	v_add_f32_dpp v12, v12, v12 row_half_mirror row_mask:0xf bank_mask:0xf bound_ctrl:1
	ds_read_b128 v[172:175], v84 offset:2944
	ds_read_b128 v[184:187], v84 offset:3712
	v_add_f32_dpp v12, v12, v12 row_mirror row_mask:0xf bank_mask:0xf bound_ctrl:1
	v_pk_fma_f32 v[2:3], v[124:125], v[12:13], v[6:7] op_sel_hi:[1,0,1] neg_lo:[0,1,0] neg_hi:[0,1,0]
	v_pk_fma_f32 v[4:5], v[126:127], v[12:13], v[8:9] op_sel_hi:[1,0,1] neg_lo:[0,1,0] neg_hi:[0,1,0]
	s_waitcnt lgkmcnt(5)
	v_pk_mul_f32 v[10:11], v[2:3], v[156:157]
	v_pk_fma_f32 v[10:11], v[4:5], v[158:159], v[10:11]
	v_pk_mul_f32 v[14:15], v[2:3], v[136:137]
	v_add_f32_e32 v12, v10, v11
	v_pk_fma_f32 v[14:15], v[4:5], v[138:139], v[14:15]
	v_add_f32_e32 v100, v14, v15
	v_add_f32_dpp v12, v12, v12 quad_perm:[1,0,3,2] row_mask:0xf bank_mask:0xf bound_ctrl:1
	v_pk_mul_f32 v[6:7], v[152:153], v[116:117] op_sel:[0,1] op_sel_hi:[1,1]
	v_pk_mul_f32 v[8:9], v[154:155], v[116:117] op_sel:[0,1] op_sel_hi:[1,1]
	v_add_f32_dpp v12, v12, v12 quad_perm:[2,3,0,1] row_mask:0xf bank_mask:0xf bound_ctrl:1
	v_pk_fma_f32 v[6:7], v[2:3], v[144:145], v[6:7]
	v_pk_fma_f32 v[8:9], v[4:5], v[146:147], v[8:9]
	v_add_f32_dpp v12, v12, v12 row_half_mirror row_mask:0xf bank_mask:0xf bound_ctrl:1
	ds_read_b128 v[34:37], v84 offset:4800
	ds_read_b128 v[22:25], v84 offset:4032
	v_add_f32_dpp v12, v12, v12 row_mirror row_mask:0xf bank_mask:0xf bound_ctrl:1
	ds_read_b128 v[30:33], v84 offset:4544
	ds_read_b128 v[26:29], v84 offset:4288
	ds_read_b128 v[38:41], v84 offset:5056
	v_pk_fma_f32 v[2:3], v[148:149], v[12:13], v[6:7] op_sel_hi:[1,0,1] neg_lo:[0,1,0] neg_hi:[0,1,0]
	v_pk_fma_f32 v[4:5], v[150:151], v[12:13], v[8:9] op_sel_hi:[1,0,1] neg_lo:[0,1,0] neg_hi:[0,1,0]
	s_waitcnt lgkmcnt(5)
	v_pk_mul_f32 v[10:11], v[2:3], v[180:181]
	v_pk_fma_f32 v[10:11], v[4:5], v[182:183], v[10:11]
	v_pk_mul_f32 v[14:15], v[2:3], v[160:161]
	v_add_f32_e32 v12, v10, v11
	v_pk_fma_f32 v[14:15], v[4:5], v[162:163], v[14:15]
	v_add_f32_e32 v101, v14, v15
	v_add_f32_dpp v12, v12, v12 quad_perm:[1,0,3,2] row_mask:0xf bank_mask:0xf bound_ctrl:1
	v_pk_mul_f32 v[6:7], v[176:177], v[118:119] op_sel_hi:[1,0]
	v_pk_mul_f32 v[8:9], v[178:179], v[118:119] op_sel_hi:[1,0]
	v_add_f32_dpp v12, v12, v12 quad_perm:[2,3,0,1] row_mask:0xf bank_mask:0xf bound_ctrl:1
	v_pk_fma_f32 v[6:7], v[2:3], v[168:169], v[6:7]
	v_pk_fma_f32 v[8:9], v[4:5], v[170:171], v[8:9]
	v_add_f32_dpp v12, v12, v12 row_half_mirror row_mask:0xf bank_mask:0xf bound_ctrl:1
	ds_read_b128 v[132:135], v84 offset:6144
	ds_read_b128 v[120:123], v84 offset:5376
	v_add_f32_dpp v12, v12, v12 row_mirror row_mask:0xf bank_mask:0xf bound_ctrl:1
	ds_read_b128 v[128:131], v84 offset:5888
	ds_read_b128 v[92:95], v96 offset:16
	ds_read_b128 v[124:127], v84 offset:5632
	ds_read_b128 v[136:139], v84 offset:6400
	v_pk_fma_f32 v[2:3], v[172:173], v[12:13], v[6:7] op_sel_hi:[1,0,1] neg_lo:[0,1,0] neg_hi:[0,1,0]
	v_pk_fma_f32 v[4:5], v[174:175], v[12:13], v[8:9] op_sel_hi:[1,0,1] neg_lo:[0,1,0] neg_hi:[0,1,0]
	s_waitcnt lgkmcnt(6)
	v_pk_mul_f32 v[10:11], v[2:3], v[34:35]
	v_pk_fma_f32 v[10:11], v[4:5], v[36:37], v[10:11]
	v_pk_mul_f32 v[14:15], v[2:3], v[184:185]
	v_add_f32_e32 v12, v10, v11
	v_pk_fma_f32 v[14:15], v[4:5], v[186:187], v[14:15]
	v_add_f32_e32 v102, v14, v15
	v_add_f32_dpp v12, v12, v12 quad_perm:[1,0,3,2] row_mask:0xf bank_mask:0xf bound_ctrl:1
	v_pk_mul_f32 v[6:7], v[30:31], v[118:119] op_sel:[0,1] op_sel_hi:[1,1]
	v_pk_mul_f32 v[8:9], v[32:33], v[118:119] op_sel:[0,1] op_sel_hi:[1,1]
	v_add_f32_dpp v12, v12, v12 quad_perm:[2,3,0,1] row_mask:0xf bank_mask:0xf bound_ctrl:1
	v_pk_fma_f32 v[6:7], v[2:3], v[22:23], v[6:7]
	v_pk_fma_f32 v[8:9], v[4:5], v[24:25], v[8:9]
	v_add_f32_dpp v12, v12, v12 row_half_mirror row_mask:0xf bank_mask:0xf bound_ctrl:1
	ds_read_b128 v[156:159], v84 offset:7488
	ds_read_b128 v[144:147], v84 offset:6720
	v_add_f32_dpp v12, v12, v12 row_mirror row_mask:0xf bank_mask:0xf bound_ctrl:1
	ds_read_b128 v[152:155], v84 offset:7232
	ds_read_b128 v[148:151], v84 offset:6976
	ds_read_b128 v[160:163], v84 offset:7744
	v_pk_fma_f32 v[2:3], v[26:27], v[12:13], v[6:7] op_sel_hi:[1,0,1] neg_lo:[0,1,0] neg_hi:[0,1,0]
	v_pk_fma_f32 v[4:5], v[28:29], v[12:13], v[8:9] op_sel_hi:[1,0,1] neg_lo:[0,1,0] neg_hi:[0,1,0]
	s_waitcnt lgkmcnt(5)
; #define LAS __attribute__((address_space(3)))
; __device__ __forceinline__ float row16_sum(float v) { v += dpp_f<0xB1>(v); v += dpp_f<0x4E>(v); v += dpp_f<0x141>(v); v += dpp_f<0x140>(v); return v; }
; __device__ __forceinline__ void rwkv_scan_unit(LAS unsigned char* lds, const float* Wd, const float* V, const bf16_t* RKKB, float* Yraw, int p, int rg, int tid) {
;     ...
;             for (int st = 0; st < SCAN_CH; ++st) {
;                 f32x4 wn = w, bn = b, kn = k, kkn = kk, rn = r; float vn = v;
;                 if (st + 1 < SCAN_CH) { const int o = (st + 1) * SCAN_STEP_B;
;                     wn = *(LAS const f32x4*)(sl + o); bn = *(LAS const f32x4*)(sl + o + 256); kn = *(LAS const f32x4*)(sl + o + 512); kkn = *(LAS const f32x4*)(sl + o + 768); rn = *(LAS const f32x4*)(sl + o + 1024);
;                     vn = *(LAS const float*)(vl + o); }
;                 float sa = (S[0] * kk[0] + S[1] * kk[1]) + (S[2] * kk[2] + S[3] * kk[3]);
;                 const f32x4 kvt = k * v;
;                 sa = -row16_sum(sa);
;                 S = S * w + (b * sa + kvt);
;                 yp[st & 15] = (S[0] * r[0] + S[1] * r[1]) + (S[2] * r[2] + S[3] * r[3]);
;                 if ((st & 15) == 15) yo[(size_t)(st - 15) * 64] = tr16_sum(yp, kq);
;                 w = wn; b = bn; k = kn; kk = kkn; r = rn; v = vn;
	v_pk_mul_f32 v[10:11], v[2:3], v[132:133]
	v_pk_fma_f32 v[10:11], v[4:5], v[134:135], v[10:11]
	v_pk_mul_f32 v[14:15], v[2:3], v[38:39]
	v_add_f32_e32 v12, v10, v11
	v_pk_fma_f32 v[14:15], v[4:5], v[40:41], v[14:15]
	v_add_f32_e32 v103, v14, v15
	v_add_f32_dpp v12, v12, v12 quad_perm:[1,0,3,2] row_mask:0xf bank_mask:0xf bound_ctrl:1
	v_pk_mul_f32 v[6:7], v[128:129], v[92:93] op_sel_hi:[1,0]
	v_pk_mul_f32 v[8:9], v[130:131], v[92:93] op_sel_hi:[1,0]
	v_add_f32_dpp v12, v12, v12 quad_perm:[2,3,0,1] row_mask:0xf bank_mask:0xf bound_ctrl:1
	v_pk_fma_f32 v[6:7], v[2:3], v[120:121], v[6:7]
	v_pk_fma_f32 v[8:9], v[4:5], v[122:123], v[8:9]
	v_add_f32_dpp v12, v12, v12 row_half_mirror row_mask:0xf bank_mask:0xf bound_ctrl:1
	ds_read_b128 v[180:183], v84 offset:8832
	ds_read_b128 v[168:171], v84 offset:8064
	v_add_f32_dpp v12, v12, v12 row_mirror row_mask:0xf bank_mask:0xf bound_ctrl:1
	ds_read_b128 v[176:179], v84 offset:8576
	ds_read_b128 v[172:175], v84 offset:8320
	ds_read_b128 v[184:187], v84 offset:9088
	v_pk_fma_f32 v[2:3], v[124:125], v[12:13], v[6:7] op_sel_hi:[1,0,1] neg_lo:[0,1,0] neg_hi:[0,1,0]
	v_pk_fma_f32 v[4:5], v[126:127], v[12:13], v[8:9] op_sel_hi:[1,0,1] neg_lo:[0,1,0] neg_hi:[0,1,0]
	s_waitcnt lgkmcnt(5)
	v_pk_mul_f32 v[10:11], v[2:3], v[156:157]
	v_pk_fma_f32 v[10:11], v[4:5], v[158:159], v[10:11]
	v_pk_mul_f32 v[14:15], v[2:3], v[136:137]
	v_add_f32_e32 v12, v10, v11
	v_pk_fma_f32 v[14:15], v[4:5], v[138:139], v[14:15]
	v_add_f32_e32 v104, v14, v15
	v_add_f32_dpp v12, v12, v12 quad_perm:[1,0,3,2] row_mask:0xf bank_mask:0xf bound_ctrl:1
	v_pk_mul_f32 v[6:7], v[152:153], v[92:93] op_sel:[0,1] op_sel_hi:[1,1]
	v_pk_mul_f32 v[8:9], v[154:155], v[92:93] op_sel:[0,1] op_sel_hi:[1,1]
	v_add_f32_dpp v12, v12, v12 quad_perm:[2,3,0,1] row_mask:0xf bank_mask:0xf bound_ctrl:1
	v_pk_fma_f32 v[6:7], v[2:3], v[144:145], v[6:7]
	v_pk_fma_f32 v[8:9], v[4:5], v[146:147], v[8:9]
	v_add_f32_dpp v12, v12, v12 row_half_mirror row_mask:0xf bank_mask:0xf bound_ctrl:1
	ds_read_b128 v[34:37], v84 offset:10176
	ds_read_b128 v[22:25], v84 offset:9408
	v_add_f32_dpp v12, v12, v12 row_mirror row_mask:0xf bank_mask:0xf bound_ctrl:1
	ds_read_b128 v[30:33], v84 offset:9920
	ds_read_b128 v[26:29], v84 offset:9664
	ds_read_b128 v[38:41], v84 offset:10432
	v_pk_fma_f32 v[2:3], v[148:149], v[12:13], v[6:7] op_sel_hi:[1,0,1] neg_lo:[0,1,0] neg_hi:[0,1,0]
	v_pk_fma_f32 v[4:5], v[150:151], v[12:13], v[8:9] op_sel_hi:[1,0,1] neg_lo:[0,1,0] neg_hi:[0,1,0]
	s_waitcnt lgkmcnt(5)
	v_pk_mul_f32 v[10:11], v[2:3], v[180:181]
	v_pk_fma_f32 v[10:11], v[4:5], v[182:183], v[10:11]
	v_pk_mul_f32 v[14:15], v[2:3], v[160:161]
	v_add_f32_e32 v12, v10, v11
	v_pk_fma_f32 v[14:15], v[4:5], v[162:163], v[14:15]
	v_add_f32_e32 v105, v14, v15
	v_add_f32_dpp v12, v12, v12 quad_perm:[1,0,3,2] row_mask:0xf bank_mask:0xf bound_ctrl:1
	v_pk_mul_f32 v[6:7], v[176:177], v[94:95] op_sel_hi:[1,0]
	v_pk_mul_f32 v[8:9], v[178:179], v[94:95] op_sel_hi:[1,0]
	v_add_f32_dpp v12, v12, v12 quad_perm:[2,3,0,1] row_mask:0xf bank_mask:0xf bound_ctrl:1
	v_pk_fma_f32 v[6:7], v[2:3], v[168:169], v[6:7]
	v_pk_fma_f32 v[8:9], v[4:5], v[170:171], v[8:9]
	v_add_f32_dpp v12, v12, v12 row_half_mirror row_mask:0xf bank_mask:0xf bound_ctrl:1
	ds_read_b128 v[132:135], v84 offset:11520
	ds_read_b128 v[120:123], v84 offset:10752
	v_add_f32_dpp v12, v12, v12 row_mirror row_mask:0xf bank_mask:0xf bound_ctrl:1
	ds_read_b128 v[128:131], v84 offset:11264
	ds_read_b128 v[116:119], v96 offset:32
	ds_read_b128 v[124:127], v84 offset:11008
	ds_read_b128 v[136:139], v84 offset:11776
	v_pk_fma_f32 v[2:3], v[172:173], v[12:13], v[6:7] op_sel_hi:[1,0,1] neg_lo:[0,1,0] neg_hi:[0,1,0]
	v_pk_fma_f32 v[4:5], v[174:175], v[12:13], v[8:9] op_sel_hi:[1,0,1] neg_lo:[0,1,0] neg_hi:[0,1,0]
	s_waitcnt lgkmcnt(6)
	v_pk_mul_f32 v[10:11], v[2:3], v[34:35]
	v_pk_fma_f32 v[10:11], v[4:5], v[36:37], v[10:11]
	v_pk_mul_f32 v[14:15], v[2:3], v[184:185]
	v_add_f32_e32 v12, v10, v11
	v_pk_fma_f32 v[14:15], v[4:5], v[186:187], v[14:15]
	v_add_f32_e32 v106, v14, v15
	v_add_f32_dpp v12, v12, v12 quad_perm:[1,0,3,2] row_mask:0xf bank_mask:0xf bound_ctrl:1
	v_pk_mul_f32 v[6:7], v[30:31], v[94:95] op_sel:[0,1] op_sel_hi:[1,1]
	v_pk_mul_f32 v[8:9], v[32:33], v[94:95] op_sel:[0,1] op_sel_hi:[1,1]
	v_add_f32_dpp v12, v12, v12 quad_perm:[2,3,0,1] row_mask:0xf bank_mask:0xf bound_ctrl:1
	v_pk_fma_f32 v[6:7], v[2:3], v[22:23], v[6:7]
	v_pk_fma_f32 v[8:9], v[4:5], v[24:25], v[8:9]
	v_add_f32_dpp v12, v12, v12 row_half_mirror row_mask:0xf bank_mask:0xf bound_ctrl:1
	ds_read_b128 v[156:159], v84 offset:12864
	ds_read_b128 v[144:147], v84 offset:12096
	v_add_f32_dpp v12, v12, v12 row_mirror row_mask:0xf bank_mask:0xf bound_ctrl:1
	ds_read_b128 v[152:155], v84 offset:12608
	ds_read_b128 v[148:151], v84 offset:12352
	ds_read_b128 v[160:163], v84 offset:13120
	v_pk_fma_f32 v[2:3], v[26:27], v[12:13], v[6:7] op_sel_hi:[1,0,1] neg_lo:[0,1,0] neg_hi:[0,1,0]
	v_pk_fma_f32 v[4:5], v[28:29], v[12:13], v[8:9] op_sel_hi:[1,0,1] neg_lo:[0,1,0] neg_hi:[0,1,0]
	s_waitcnt lgkmcnt(5)
; #define LAS __attribute__((address_space(3)))
; __device__ __forceinline__ float row16_sum(float v) { v += dpp_f<0xB1>(v); v += dpp_f<0x4E>(v); v += dpp_f<0x141>(v); v += dpp_f<0x140>(v); return v; }
; __device__ __forceinline__ void rwkv_scan_unit(LAS unsigned char* lds, const float* Wd, const float* V, const bf16_t* RKKB, float* Yraw, int p, int rg, int tid) {
;     ...
;             for (int st = 0; st < SCAN_CH; ++st) {
;                 f32x4 wn = w, bn = b, kn = k, kkn = kk, rn = r; float vn = v;
;                 if (st + 1 < SCAN_CH) { const int o = (st + 1) * SCAN_STEP_B;
;                     wn = *(LAS const f32x4*)(sl + o); bn = *(LAS const f32x4*)(sl + o + 256); kn = *(LAS const f32x4*)(sl + o + 512); kkn = *(LAS const f32x4*)(sl + o + 768); rn = *(LAS const f32x4*)(sl + o + 1024);
;                     vn = *(LAS const float*)(vl + o); }
;                 float sa = (S[0] * kk[0] + S[1] * kk[1]) + (S[2] * kk[2] + S[3] * kk[3]);
;                 const f32x4 kvt = k * v;
;                 sa = -row16_sum(sa);
;                 S = S * w + (b * sa + kvt);
;                 yp[st & 15] = (S[0] * r[0] + S[1] * r[1]) + (S[2] * r[2] + S[3] * r[3]);
;                 if ((st & 15) == 15) yo[(size_t)(st - 15) * 64] = tr16_sum(yp, kq);
;                 w = wn; b = bn; k = kn; kk = kkn; r = rn; v = vn;
	v_pk_mul_f32 v[10:11], v[2:3], v[132:133]
	v_pk_fma_f32 v[10:11], v[4:5], v[134:135], v[10:11]
	v_pk_mul_f32 v[14:15], v[2:3], v[38:39]
	v_add_f32_e32 v12, v10, v11
	v_pk_fma_f32 v[14:15], v[4:5], v[40:41], v[14:15]
	v_add_f32_e32 v107, v14, v15
	v_add_f32_dpp v12, v12, v12 quad_perm:[1,0,3,2] row_mask:0xf bank_mask:0xf bound_ctrl:1
	v_pk_mul_f32 v[6:7], v[128:129], v[116:117] op_sel_hi:[1,0]
	v_pk_mul_f32 v[8:9], v[130:131], v[116:117] op_sel_hi:[1,0]
	v_add_f32_dpp v12, v12, v12 quad_perm:[2,3,0,1] row_mask:0xf bank_mask:0xf bound_ctrl:1
	v_pk_fma_f32 v[6:7], v[2:3], v[120:121], v[6:7]
	v_pk_fma_f32 v[8:9], v[4:5], v[122:123], v[8:9]
	v_add_f32_dpp v12, v12, v12 row_half_mirror row_mask:0xf bank_mask:0xf bound_ctrl:1
	ds_read_b128 v[180:183], v84 offset:14208
	ds_read_b128 v[168:171], v84 offset:13440
	v_add_f32_dpp v12, v12, v12 row_mirror row_mask:0xf bank_mask:0xf bound_ctrl:1
	ds_read_b128 v[176:179], v84 offset:13952
	ds_read_b128 v[172:175], v84 offset:13696
	ds_read_b128 v[184:187], v84 offset:14464
	v_pk_fma_f32 v[2:3], v[124:125], v[12:13], v[6:7] op_sel_hi:[1,0,1] neg_lo:[0,1,0] neg_hi:[0,1,0]
	v_pk_fma_f32 v[4:5], v[126:127], v[12:13], v[8:9] op_sel_hi:[1,0,1] neg_lo:[0,1,0] neg_hi:[0,1,0]
	s_waitcnt lgkmcnt(5)
	v_pk_mul_f32 v[10:11], v[2:3], v[156:157]
	v_pk_fma_f32 v[10:11], v[4:5], v[158:159], v[10:11]
	v_pk_mul_f32 v[14:15], v[2:3], v[136:137]
	v_add_f32_e32 v12, v10, v11
	v_pk_fma_f32 v[14:15], v[4:5], v[138:139], v[14:15]
	v_add_f32_e32 v44, v14, v15
	v_add_f32_dpp v12, v12, v12 quad_perm:[1,0,3,2] row_mask:0xf bank_mask:0xf bound_ctrl:1
	v_add_f32_dpp v100, v100, v100 row_mirror row_mask:0xf bank_mask:0x3 bound_ctrl:1
	v_add_f32_dpp v100, v44, v44 row_mirror row_mask:0xf bank_mask:0xc bound_ctrl:1
	v_add_f32_dpp v12, v12, v12 quad_perm:[2,3,0,1] row_mask:0xf bank_mask:0xf bound_ctrl:1
	v_pk_mul_f32 v[6:7], v[152:153], v[116:117] op_sel:[0,1] op_sel_hi:[1,1]
	v_pk_mul_f32 v[8:9], v[154:155], v[116:117] op_sel:[0,1] op_sel_hi:[1,1]
	v_add_f32_dpp v12, v12, v12 row_half_mirror row_mask:0xf bank_mask:0xf bound_ctrl:1
	v_pk_fma_f32 v[6:7], v[2:3], v[144:145], v[6:7]
	v_pk_fma_f32 v[8:9], v[4:5], v[146:147], v[8:9]
	v_add_f32_dpp v12, v12, v12 row_mirror row_mask:0xf bank_mask:0xf bound_ctrl:1
	ds_read_b128 v[34:37], v84 offset:15552
	ds_read_b128 v[22:25], v84 offset:14784
	ds_read_b128 v[30:33], v84 offset:15296
	ds_read_b128 v[26:29], v84 offset:15040
	ds_read_b128 v[38:41], v84 offset:15808
	v_pk_fma_f32 v[2:3], v[148:149], v[12:13], v[6:7] op_sel_hi:[1,0,1] neg_lo:[0,1,0] neg_hi:[0,1,0]
	v_pk_fma_f32 v[4:5], v[150:151], v[12:13], v[8:9] op_sel_hi:[1,0,1] neg_lo:[0,1,0] neg_hi:[0,1,0]
	s_waitcnt lgkmcnt(5)
	v_pk_mul_f32 v[10:11], v[2:3], v[180:181]
	v_pk_fma_f32 v[10:11], v[4:5], v[182:183], v[10:11]
	v_pk_mul_f32 v[14:15], v[2:3], v[160:161]
	v_add_f32_e32 v12, v10, v11
	v_pk_fma_f32 v[14:15], v[4:5], v[162:163], v[14:15]
	v_add_f32_e32 v44, v14, v15
	v_add_f32_dpp v12, v12, v12 quad_perm:[1,0,3,2] row_mask:0xf bank_mask:0xf bound_ctrl:1
	v_add_f32_dpp v101, v101, v101 row_mirror row_mask:0xf bank_mask:0x3 bound_ctrl:1
	v_add_f32_dpp v101, v44, v44 row_mirror row_mask:0xf bank_mask:0xc bound_ctrl:1
	v_add_f32_dpp v12, v12, v12 quad_perm:[2,3,0,1] row_mask:0xf bank_mask:0xf bound_ctrl:1
	v_pk_mul_f32 v[6:7], v[176:177], v[118:119] op_sel_hi:[1,0]
	v_pk_mul_f32 v[8:9], v[178:179], v[118:119] op_sel_hi:[1,0]
	v_add_f32_dpp v12, v12, v12 row_half_mirror row_mask:0xf bank_mask:0xf bound_ctrl:1
	v_pk_fma_f32 v[6:7], v[2:3], v[168:169], v[6:7]
	v_pk_fma_f32 v[8:9], v[4:5], v[170:171], v[8:9]
	v_add_f32_dpp v12, v12, v12 row_mirror row_mask:0xf bank_mask:0xf bound_ctrl:1
	ds_read_b128 v[132:135], v84 offset:16896
	ds_read_b128 v[120:123], v84 offset:16128
	ds_read_b128 v[128:131], v84 offset:16640
	ds_read_b128 v[92:95], v96 offset:48
	ds_read_b128 v[124:127], v84 offset:16384
	ds_read_b128 v[136:139], v84 offset:17152
	v_pk_fma_f32 v[2:3], v[172:173], v[12:13], v[6:7] op_sel_hi:[1,0,1] neg_lo:[0,1,0] neg_hi:[0,1,0]
	v_pk_fma_f32 v[4:5], v[174:175], v[12:13], v[8:9] op_sel_hi:[1,0,1] neg_lo:[0,1,0] neg_hi:[0,1,0]
	s_waitcnt lgkmcnt(6)
	v_pk_mul_f32 v[10:11], v[2:3], v[34:35]
	v_pk_fma_f32 v[10:11], v[4:5], v[36:37], v[10:11]
	v_pk_mul_f32 v[14:15], v[2:3], v[184:185]
	v_add_f32_e32 v12, v10, v11
	v_pk_fma_f32 v[14:15], v[4:5], v[186:187], v[14:15]
	v_add_f32_e32 v44, v14, v15
	v_add_f32_dpp v12, v12, v12 quad_perm:[1,0,3,2] row_mask:0xf bank_mask:0xf bound_ctrl:1
	v_add_f32_dpp v102, v102, v102 row_mirror row_mask:0xf bank_mask:0x3 bound_ctrl:1
	v_add_f32_dpp v102, v44, v44 row_mirror row_mask:0xf bank_mask:0xc bound_ctrl:1
	v_add_f32_dpp v12, v12, v12 quad_perm:[2,3,0,1] row_mask:0xf bank_mask:0xf bound_ctrl:1
	v_pk_mul_f32 v[6:7], v[30:31], v[118:119] op_sel:[0,1] op_sel_hi:[1,1]
	v_pk_mul_f32 v[8:9], v[32:33], v[118:119] op_sel:[0,1] op_sel_hi:[1,1]
	v_add_f32_dpp v12, v12, v12 row_half_mirror row_mask:0xf bank_mask:0xf bound_ctrl:1
	v_pk_fma_f32 v[6:7], v[2:3], v[22:23], v[6:7]
	v_pk_fma_f32 v[8:9], v[4:5], v[24:25], v[8:9]
	v_add_f32_dpp v12, v12, v12 row_mirror row_mask:0xf bank_mask:0xf bound_ctrl:1
	ds_read_b128 v[156:159], v84 offset:18240
	ds_read_b128 v[144:147], v84 offset:17472
	ds_read_b128 v[152:155], v84 offset:17984
	ds_read_b128 v[148:151], v84 offset:17728
	ds_read_b128 v[160:163], v84 offset:18496
	v_pk_fma_f32 v[2:3], v[26:27], v[12:13], v[6:7] op_sel_hi:[1,0,1] neg_lo:[0,1,0] neg_hi:[0,1,0]
	v_pk_fma_f32 v[4:5], v[28:29], v[12:13], v[8:9] op_sel_hi:[1,0,1] neg_lo:[0,1,0] neg_hi:[0,1,0]
	s_waitcnt lgkmcnt(5)
; #define LAS __attribute__((address_space(3)))
; __device__ __forceinline__ float row16_sum(float v) { v += dpp_f<0xB1>(v); v += dpp_f<0x4E>(v); v += dpp_f<0x141>(v); v += dpp_f<0x140>(v); return v; }
; __device__ __forceinline__ void rwkv_scan_unit(LAS unsigned char* lds, const float* Wd, const float* V, const bf16_t* RKKB, float* Yraw, int p, int rg, int tid) {
;     ...
;             for (int st = 0; st < SCAN_CH; ++st) {
;                 f32x4 wn = w, bn = b, kn = k, kkn = kk, rn = r; float vn = v;
;                 if (st + 1 < SCAN_CH) { const int o = (st + 1) * SCAN_STEP_B;
;                     wn = *(LAS const f32x4*)(sl + o); bn = *(LAS const f32x4*)(sl + o + 256); kn = *(LAS const f32x4*)(sl + o + 512); kkn = *(LAS const f32x4*)(sl + o + 768); rn = *(LAS const f32x4*)(sl + o + 1024);
;                     vn = *(LAS const float*)(vl + o); }
;                 float sa = (S[0] * kk[0] + S[1] * kk[1]) + (S[2] * kk[2] + S[3] * kk[3]);
;                 const f32x4 kvt = k * v;
;                 sa = -row16_sum(sa);
;                 S = S * w + (b * sa + kvt);
;                 yp[st & 15] = (S[0] * r[0] + S[1] * r[1]) + (S[2] * r[2] + S[3] * r[3]);
;                 if ((st & 15) == 15) yo[(size_t)(st - 15) * 64] = tr16_sum(yp, kq);
;                 w = wn; b = bn; k = kn; kk = kkn; r = rn; v = vn;
	v_pk_mul_f32 v[10:11], v[2:3], v[132:133]
	v_pk_fma_f32 v[10:11], v[4:5], v[134:135], v[10:11]
	v_pk_mul_f32 v[14:15], v[2:3], v[38:39]
	v_add_f32_e32 v12, v10, v11
	v_pk_fma_f32 v[14:15], v[4:5], v[40:41], v[14:15]
	v_add_f32_e32 v44, v14, v15
	v_add_f32_dpp v12, v12, v12 quad_perm:[1,0,3,2] row_mask:0xf bank_mask:0xf bound_ctrl:1
	v_add_f32_dpp v103, v103, v103 row_mirror row_mask:0xf bank_mask:0x3 bound_ctrl:1
	v_add_f32_dpp v103, v44, v44 row_mirror row_mask:0xf bank_mask:0xc bound_ctrl:1
	v_add_f32_dpp v12, v12, v12 quad_perm:[2,3,0,1] row_mask:0xf bank_mask:0xf bound_ctrl:1
	v_pk_mul_f32 v[6:7], v[128:129], v[92:93] op_sel_hi:[1,0]
	v_pk_mul_f32 v[8:9], v[130:131], v[92:93] op_sel_hi:[1,0]
	v_add_f32_dpp v12, v12, v12 row_half_mirror row_mask:0xf bank_mask:0xf bound_ctrl:1
	v_pk_fma_f32 v[6:7], v[2:3], v[120:121], v[6:7]
	v_pk_fma_f32 v[8:9], v[4:5], v[122:123], v[8:9]
	v_add_f32_dpp v12, v12, v12 row_mirror row_mask:0xf bank_mask:0xf bound_ctrl:1
	ds_read_b128 v[180:183], v84 offset:19584
	ds_read_b128 v[168:171], v84 offset:18816
	ds_read_b128 v[176:179], v84 offset:19328
	ds_read_b128 v[172:175], v84 offset:19072
	ds_read_b128 v[184:187], v84 offset:19840
	v_pk_fma_f32 v[2:3], v[124:125], v[12:13], v[6:7] op_sel_hi:[1,0,1] neg_lo:[0,1,0] neg_hi:[0,1,0]
	v_pk_fma_f32 v[4:5], v[126:127], v[12:13], v[8:9] op_sel_hi:[1,0,1] neg_lo:[0,1,0] neg_hi:[0,1,0]
	s_waitcnt lgkmcnt(5)
	v_pk_mul_f32 v[10:11], v[2:3], v[156:157]
	v_pk_fma_f32 v[10:11], v[4:5], v[158:159], v[10:11]
	v_pk_mul_f32 v[14:15], v[2:3], v[136:137]
	v_add_f32_e32 v12, v10, v11
	v_pk_fma_f32 v[14:15], v[4:5], v[138:139], v[14:15]
	v_add_f32_e32 v44, v14, v15
	v_add_f32_dpp v12, v12, v12 quad_perm:[1,0,3,2] row_mask:0xf bank_mask:0xf bound_ctrl:1
	v_add_f32_dpp v104, v104, v104 row_mirror row_mask:0xf bank_mask:0x3 bound_ctrl:1
	v_add_f32_dpp v104, v44, v44 row_mirror row_mask:0xf bank_mask:0xc bound_ctrl:1
	v_add_f32_dpp v12, v12, v12 quad_perm:[2,3,0,1] row_mask:0xf bank_mask:0xf bound_ctrl:1
	v_pk_mul_f32 v[6:7], v[152:153], v[92:93] op_sel:[0,1] op_sel_hi:[1,1]
	v_pk_mul_f32 v[8:9], v[154:155], v[92:93] op_sel:[0,1] op_sel_hi:[1,1]
	v_add_f32_dpp v12, v12, v12 row_half_mirror row_mask:0xf bank_mask:0xf bound_ctrl:1
	v_pk_fma_f32 v[6:7], v[2:3], v[144:145], v[6:7]
	v_pk_fma_f32 v[8:9], v[4:5], v[146:147], v[8:9]
	v_add_f32_dpp v12, v12, v12 row_mirror row_mask:0xf bank_mask:0xf bound_ctrl:1
	ds_read_b128 v[34:37], v84 offset:20928
	ds_read_b128 v[22:25], v84 offset:20160
	ds_read_b128 v[30:33], v84 offset:20672
	ds_read_b128 v[26:29], v84 offset:20416
	ds_read_b128 v[38:41], v84 offset:21184
	v_pk_fma_f32 v[2:3], v[148:149], v[12:13], v[6:7] op_sel_hi:[1,0,1] neg_lo:[0,1,0] neg_hi:[0,1,0]
	v_pk_fma_f32 v[4:5], v[150:151], v[12:13], v[8:9] op_sel_hi:[1,0,1] neg_lo:[0,1,0] neg_hi:[0,1,0]
	s_waitcnt lgkmcnt(5)
	v_pk_mul_f32 v[10:11], v[2:3], v[180:181]
	v_pk_fma_f32 v[10:11], v[4:5], v[182:183], v[10:11]
	v_pk_mul_f32 v[14:15], v[2:3], v[160:161]
	v_add_f32_e32 v12, v10, v11
	v_pk_fma_f32 v[14:15], v[4:5], v[162:163], v[14:15]
	v_add_f32_e32 v44, v14, v15
	v_add_f32_dpp v12, v12, v12 quad_perm:[1,0,3,2] row_mask:0xf bank_mask:0xf bound_ctrl:1
	v_add_f32_dpp v105, v105, v105 row_mirror row_mask:0xf bank_mask:0x3 bound_ctrl:1
	v_add_f32_dpp v105, v44, v44 row_mirror row_mask:0xf bank_mask:0xc bound_ctrl:1
	v_add_f32_dpp v12, v12, v12 quad_perm:[2,3,0,1] row_mask:0xf bank_mask:0xf bound_ctrl:1
	v_pk_mul_f32 v[6:7], v[176:177], v[94:95] op_sel_hi:[1,0]
	v_pk_mul_f32 v[8:9], v[178:179], v[94:95] op_sel_hi:[1,0]
	v_add_f32_dpp v12, v12, v12 row_half_mirror row_mask:0xf bank_mask:0xf bound_ctrl:1
	v_pk_fma_f32 v[6:7], v[2:3], v[168:169], v[6:7]
	v_pk_fma_f32 v[8:9], v[4:5], v[170:171], v[8:9]
	v_add_f32_dpp v12, v12, v12 row_mirror row_mask:0xf bank_mask:0xf bound_ctrl:1
	ds_read_b128 v[132:135], v84 offset:22272
	ds_read_b128 v[120:123], v84 offset:21504
	ds_read_b128 v[128:131], v84 offset:22016
	ds_read_b128 v[116:119], v96 offset:64
	ds_read_b128 v[124:127], v84 offset:21760
	ds_read_b128 v[136:139], v84 offset:22528
	v_pk_fma_f32 v[2:3], v[172:173], v[12:13], v[6:7] op_sel_hi:[1,0,1] neg_lo:[0,1,0] neg_hi:[0,1,0]
	v_pk_fma_f32 v[4:5], v[174:175], v[12:13], v[8:9] op_sel_hi:[1,0,1] neg_lo:[0,1,0] neg_hi:[0,1,0]
	s_waitcnt lgkmcnt(6)
	v_pk_mul_f32 v[10:11], v[2:3], v[34:35]
	v_pk_fma_f32 v[10:11], v[4:5], v[36:37], v[10:11]
	v_pk_mul_f32 v[14:15], v[2:3], v[184:185]
	v_add_f32_e32 v12, v10, v11
	v_pk_fma_f32 v[14:15], v[4:5], v[186:187], v[14:15]
	v_add_f32_e32 v44, v14, v15
	v_add_f32_dpp v12, v12, v12 quad_perm:[1,0,3,2] row_mask:0xf bank_mask:0xf bound_ctrl:1
	v_add_f32_dpp v106, v106, v106 row_mirror row_mask:0xf bank_mask:0x3 bound_ctrl:1
	v_add_f32_dpp v106, v44, v44 row_mirror row_mask:0xf bank_mask:0xc bound_ctrl:1
	v_add_f32_dpp v12, v12, v12 quad_perm:[2,3,0,1] row_mask:0xf bank_mask:0xf bound_ctrl:1
	v_pk_mul_f32 v[6:7], v[30:31], v[94:95] op_sel:[0,1] op_sel_hi:[1,1]
	v_pk_mul_f32 v[8:9], v[32:33], v[94:95] op_sel:[0,1] op_sel_hi:[1,1]
	v_add_f32_dpp v12, v12, v12 row_half_mirror row_mask:0xf bank_mask:0xf bound_ctrl:1
	v_pk_fma_f32 v[6:7], v[2:3], v[22:23], v[6:7]
	v_pk_fma_f32 v[8:9], v[4:5], v[24:25], v[8:9]
	v_add_f32_dpp v12, v12, v12 row_mirror row_mask:0xf bank_mask:0xf bound_ctrl:1
	ds_read_b128 v[156:159], v84 offset:23616
	ds_read_b128 v[144:147], v84 offset:22848
	ds_read_b128 v[152:155], v84 offset:23360
	ds_read_b128 v[148:151], v84 offset:23104
	ds_read_b128 v[160:163], v84 offset:23872
	v_pk_fma_f32 v[2:3], v[26:27], v[12:13], v[6:7] op_sel_hi:[1,0,1] neg_lo:[0,1,0] neg_hi:[0,1,0]
	v_pk_fma_f32 v[4:5], v[28:29], v[12:13], v[8:9] op_sel_hi:[1,0,1] neg_lo:[0,1,0] neg_hi:[0,1,0]
	s_waitcnt lgkmcnt(5)
; #define LAS __attribute__((address_space(3)))
; __device__ __forceinline__ float row16_sum(float v) { v += dpp_f<0xB1>(v); v += dpp_f<0x4E>(v); v += dpp_f<0x141>(v); v += dpp_f<0x140>(v); return v; }
; __device__ __forceinline__ void rwkv_scan_unit(LAS unsigned char* lds, const float* Wd, const float* V, const bf16_t* RKKB, float* Yraw, int p, int rg, int tid) {
;     ...
;             for (int st = 0; st < SCAN_CH; ++st) {
;                 f32x4 wn = w, bn = b, kn = k, kkn = kk, rn = r; float vn = v;
;                 if (st + 1 < SCAN_CH) { const int o = (st + 1) * SCAN_STEP_B;
;                     wn = *(LAS const f32x4*)(sl + o); bn = *(LAS const f32x4*)(sl + o + 256); kn = *(LAS const f32x4*)(sl + o + 512); kkn = *(LAS const f32x4*)(sl + o + 768); rn = *(LAS const f32x4*)(sl + o + 1024);
;                     vn = *(LAS const float*)(vl + o); }
;                 float sa = (S[0] * kk[0] + S[1] * kk[1]) + (S[2] * kk[2] + S[3] * kk[3]);
;                 const f32x4 kvt = k * v;
;                 sa = -row16_sum(sa);
;                 S = S * w + (b * sa + kvt);
;                 yp[st & 15] = (S[0] * r[0] + S[1] * r[1]) + (S[2] * r[2] + S[3] * r[3]);
;                 if ((st & 15) == 15) yo[(size_t)(st - 15) * 64] = tr16_sum(yp, kq);
;                 w = wn; b = bn; k = kn; kk = kkn; r = rn; v = vn;
	v_pk_mul_f32 v[10:11], v[2:3], v[132:133]
	v_pk_fma_f32 v[10:11], v[4:5], v[134:135], v[10:11]
	v_pk_mul_f32 v[14:15], v[2:3], v[38:39]
	v_add_f32_e32 v12, v10, v11
	v_pk_fma_f32 v[14:15], v[4:5], v[40:41], v[14:15]
	v_add_f32_e32 v44, v14, v15
	v_add_f32_dpp v107, v107, v107 row_mirror row_mask:0xf bank_mask:0x3 bound_ctrl:1
	s_nop 0
	v_add_f32_dpp v107, v44, v44 row_mirror row_mask:0xf bank_mask:0xc bound_ctrl:1
	v_add_f32_dpp v12, v12, v12 quad_perm:[1,0,3,2] row_mask:0xf bank_mask:0xf bound_ctrl:1
	v_pk_mul_f32 v[6:7], v[128:129], v[116:117] op_sel_hi:[1,0]
	v_pk_mul_f32 v[8:9], v[130:131], v[116:117] op_sel_hi:[1,0]
	v_pk_fma_f32 v[6:7], v[2:3], v[120:121], v[6:7]
	v_pk_fma_f32 v[8:9], v[4:5], v[122:123], v[8:9]
	v_add_f32_dpp v12, v12, v12 quad_perm:[2,3,0,1] row_mask:0xf bank_mask:0xf bound_ctrl:1
	ds_read_b128 v[180:183], v84 offset:24960
	ds_read_b128 v[168:171], v84 offset:24192
	ds_read_b128 v[176:179], v84 offset:24704
	ds_read_b128 v[172:175], v84 offset:24448
	v_add_f32_dpp v12, v12, v12 row_half_mirror row_mask:0xf bank_mask:0xf bound_ctrl:1
	ds_read_b128 v[184:187], v84 offset:25216
	v_add_f32_dpp v100, v100, v100 row_half_mirror row_mask:0xf bank_mask:0x5 bound_ctrl:1
	v_add_f32_dpp v100, v104, v104 row_half_mirror row_mask:0xf bank_mask:0xa bound_ctrl:1
	v_add_f32_dpp v101, v101, v101 row_half_mirror row_mask:0xf bank_mask:0x5 bound_ctrl:1
	v_add_f32_dpp v12, v12, v12 row_mirror row_mask:0xf bank_mask:0xf bound_ctrl:1
	v_add_f32_dpp v101, v105, v105 row_half_mirror row_mask:0xf bank_mask:0xa bound_ctrl:1
	v_add_f32_dpp v102, v102, v102 row_half_mirror row_mask:0xf bank_mask:0x5 bound_ctrl:1
	v_add_f32_dpp v102, v106, v106 row_half_mirror row_mask:0xf bank_mask:0xa bound_ctrl:1
	v_add_f32_dpp v103, v103, v103 row_half_mirror row_mask:0xf bank_mask:0x5 bound_ctrl:1
	v_add_f32_dpp v103, v107, v107 row_half_mirror row_mask:0xf bank_mask:0xa bound_ctrl:1
	v_cndmask_b32_e64 v16, v102, v100, s[8:9]
	v_pk_fma_f32 v[2:3], v[124:125], v[12:13], v[6:7] op_sel_hi:[1,0,1] neg_lo:[0,1,0] neg_hi:[0,1,0]
	v_pk_fma_f32 v[4:5], v[126:127], v[12:13], v[8:9] op_sel_hi:[1,0,1] neg_lo:[0,1,0] neg_hi:[0,1,0]
	s_waitcnt lgkmcnt(5)
	v_pk_mul_f32 v[10:11], v[2:3], v[156:157]
	v_pk_fma_f32 v[10:11], v[4:5], v[158:159], v[10:11]
	v_pk_mul_f32 v[14:15], v[2:3], v[136:137]
	v_add_f32_e32 v12, v10, v11
	v_pk_fma_f32 v[14:15], v[4:5], v[138:139], v[14:15]
	v_add_f32_e32 v108, v14, v15
	v_pk_mul_f32 v[6:7], v[152:153], v[116:117] op_sel:[0,1] op_sel_hi:[1,1]
	v_pk_mul_f32 v[8:9], v[154:155], v[116:117] op_sel:[0,1] op_sel_hi:[1,1]
	v_add_f32_dpp v12, v12, v12 quad_perm:[1,0,3,2] row_mask:0xf bank_mask:0xf bound_ctrl:1
	v_pk_fma_f32 v[6:7], v[2:3], v[144:145], v[6:7]
	v_pk_fma_f32 v[8:9], v[4:5], v[146:147], v[8:9]
	ds_read_b128 v[34:37], v84 offset:26304
	ds_read_b128 v[22:25], v84 offset:25536
	v_add_f32_dpp v12, v12, v12 quad_perm:[2,3,0,1] row_mask:0xf bank_mask:0xf bound_ctrl:1
	ds_read_b128 v[30:33], v84 offset:26048
	ds_read_b128 v[26:29], v84 offset:25792
	ds_read_b128 v[38:41], v84 offset:26560
	v_cndmask_b32_e64 v17, v100, v102, s[8:9]
	v_add_f32_dpp v12, v12, v12 row_half_mirror row_mask:0xf bank_mask:0xf bound_ctrl:1
	s_nop 0
	v_add_f32_dpp v16, v17, v16 quad_perm:[2,3,0,1] row_mask:0xf bank_mask:0xf bound_ctrl:1
	v_cndmask_b32_e64 v18, v103, v101, s[8:9]
	v_cndmask_b32_e64 v19, v101, v103, s[8:9]
	s_nop 1
	v_add_f32_dpp v18, v19, v18 quad_perm:[2,3,0,1] row_mask:0xf bank_mask:0xf bound_ctrl:1
	v_add_f32_dpp v12, v12, v12 row_mirror row_mask:0xf bank_mask:0xf bound_ctrl:1
	v_cndmask_b32_e64 v17, v18, v16, s[10:11]
	v_cndmask_b32_e64 v19, v16, v18, s[10:11]
	s_nop 1
	v_add_f32_dpp v17, v19, v17 quad_perm:[1,0,3,2] row_mask:0xf bank_mask:0xf bound_ctrl:1
	global_store_dword v[88:89], v17, off
	v_pk_fma_f32 v[2:3], v[148:149], v[12:13], v[6:7] op_sel_hi:[1,0,1] neg_lo:[0,1,0] neg_hi:[0,1,0]
	v_pk_fma_f32 v[4:5], v[150:151], v[12:13], v[8:9] op_sel_hi:[1,0,1] neg_lo:[0,1,0] neg_hi:[0,1,0]
	s_waitcnt lgkmcnt(5)
	v_pk_mul_f32 v[10:11], v[2:3], v[180:181]
	v_pk_fma_f32 v[10:11], v[4:5], v[182:183], v[10:11]
	v_pk_mul_f32 v[14:15], v[2:3], v[160:161]
	v_add_f32_e32 v12, v10, v11
	v_pk_fma_f32 v[14:15], v[4:5], v[162:163], v[14:15]
	v_add_f32_e32 v109, v14, v15
	v_add_f32_dpp v12, v12, v12 quad_perm:[1,0,3,2] row_mask:0xf bank_mask:0xf bound_ctrl:1
	v_pk_mul_f32 v[6:7], v[176:177], v[118:119] op_sel_hi:[1,0]
	v_pk_mul_f32 v[8:9], v[178:179], v[118:119] op_sel_hi:[1,0]
	v_add_f32_dpp v12, v12, v12 quad_perm:[2,3,0,1] row_mask:0xf bank_mask:0xf bound_ctrl:1
	v_pk_fma_f32 v[6:7], v[2:3], v[168:169], v[6:7]
	v_pk_fma_f32 v[8:9], v[4:5], v[170:171], v[8:9]
	v_add_f32_dpp v12, v12, v12 row_half_mirror row_mask:0xf bank_mask:0xf bound_ctrl:1
	ds_read_b128 v[132:135], v84 offset:27648
	ds_read_b128 v[120:123], v84 offset:26880
	v_add_f32_dpp v12, v12, v12 row_mirror row_mask:0xf bank_mask:0xf bound_ctrl:1
	ds_read_b128 v[128:131], v84 offset:27392
	ds_read_b128 v[92:95], v96 offset:80
	ds_read_b128 v[124:127], v84 offset:27136
	ds_read_b128 v[136:139], v84 offset:27904
	v_pk_fma_f32 v[2:3], v[172:173], v[12:13], v[6:7] op_sel_hi:[1,0,1] neg_lo:[0,1,0] neg_hi:[0,1,0]
	v_pk_fma_f32 v[4:5], v[174:175], v[12:13], v[8:9] op_sel_hi:[1,0,1] neg_lo:[0,1,0] neg_hi:[0,1,0]
	s_waitcnt lgkmcnt(6)
; #define LAS __attribute__((address_space(3)))
; __device__ __forceinline__ float row16_sum(float v) { v += dpp_f<0xB1>(v); v += dpp_f<0x4E>(v); v += dpp_f<0x141>(v); v += dpp_f<0x140>(v); return v; }
; __device__ __forceinline__ void rwkv_scan_unit(LAS unsigned char* lds, const float* Wd, const float* V, const bf16_t* RKKB, float* Yraw, int p, int rg, int tid) {
;     ...
;             for (int st = 0; st < SCAN_CH; ++st) {
;                 f32x4 wn = w, bn = b, kn = k, kkn = kk, rn = r; float vn = v;
;                 if (st + 1 < SCAN_CH) { const int o = (st + 1) * SCAN_STEP_B;
;                     wn = *(LAS const f32x4*)(sl + o); bn = *(LAS const f32x4*)(sl + o + 256); kn = *(LAS const f32x4*)(sl + o + 512); kkn = *(LAS const f32x4*)(sl + o + 768); rn = *(LAS const f32x4*)(sl + o + 1024);
;                     vn = *(LAS const float*)(vl + o); }
;                 float sa = (S[0] * kk[0] + S[1] * kk[1]) + (S[2] * kk[2] + S[3] * kk[3]);
;                 const f32x4 kvt = k * v;
;                 sa = -row16_sum(sa);
;                 S = S * w + (b * sa + kvt);
;                 yp[st & 15] = (S[0] * r[0] + S[1] * r[1]) + (S[2] * r[2] + S[3] * r[3]);
;                 if ((st & 15) == 15) yo[(size_t)(st - 15) * 64] = tr16_sum(yp, kq);
;                 w = wn; b = bn; k = kn; kk = kkn; r = rn; v = vn;
	v_pk_mul_f32 v[10:11], v[2:3], v[34:35]
	v_pk_fma_f32 v[10:11], v[4:5], v[36:37], v[10:11]
	v_pk_mul_f32 v[14:15], v[2:3], v[184:185]
	v_add_f32_e32 v12, v10, v11
	v_pk_fma_f32 v[14:15], v[4:5], v[186:187], v[14:15]
	v_add_f32_e32 v110, v14, v15
	v_add_f32_dpp v12, v12, v12 quad_perm:[1,0,3,2] row_mask:0xf bank_mask:0xf bound_ctrl:1
	v_pk_mul_f32 v[6:7], v[30:31], v[118:119] op_sel:[0,1] op_sel_hi:[1,1]
	v_pk_mul_f32 v[8:9], v[32:33], v[118:119] op_sel:[0,1] op_sel_hi:[1,1]
	v_add_f32_dpp v12, v12, v12 quad_perm:[2,3,0,1] row_mask:0xf bank_mask:0xf bound_ctrl:1
	v_pk_fma_f32 v[6:7], v[2:3], v[22:23], v[6:7]
	v_pk_fma_f32 v[8:9], v[4:5], v[24:25], v[8:9]
	v_add_f32_dpp v12, v12, v12 row_half_mirror row_mask:0xf bank_mask:0xf bound_ctrl:1
	ds_read_b128 v[156:159], v84 offset:28992
	ds_read_b128 v[144:147], v84 offset:28224
	v_add_f32_dpp v12, v12, v12 row_mirror row_mask:0xf bank_mask:0xf bound_ctrl:1
	ds_read_b128 v[152:155], v84 offset:28736
	ds_read_b128 v[148:151], v84 offset:28480
	ds_read_b128 v[160:163], v84 offset:29248
	v_pk_fma_f32 v[2:3], v[26:27], v[12:13], v[6:7] op_sel_hi:[1,0,1] neg_lo:[0,1,0] neg_hi:[0,1,0]
	v_pk_fma_f32 v[4:5], v[28:29], v[12:13], v[8:9] op_sel_hi:[1,0,1] neg_lo:[0,1,0] neg_hi:[0,1,0]
	s_waitcnt lgkmcnt(5)
	v_pk_mul_f32 v[10:11], v[2:3], v[132:133]
	v_pk_fma_f32 v[10:11], v[4:5], v[134:135], v[10:11]
	v_pk_mul_f32 v[14:15], v[2:3], v[38:39]
	v_add_f32_e32 v12, v10, v11
	v_pk_fma_f32 v[14:15], v[4:5], v[40:41], v[14:15]
	v_add_f32_e32 v111, v14, v15
	v_add_f32_dpp v12, v12, v12 quad_perm:[1,0,3,2] row_mask:0xf bank_mask:0xf bound_ctrl:1
	v_pk_mul_f32 v[6:7], v[128:129], v[92:93] op_sel_hi:[1,0]
	v_pk_mul_f32 v[8:9], v[130:131], v[92:93] op_sel_hi:[1,0]
	v_add_f32_dpp v12, v12, v12 quad_perm:[2,3,0,1] row_mask:0xf bank_mask:0xf bound_ctrl:1
	v_pk_fma_f32 v[6:7], v[2:3], v[120:121], v[6:7]
	v_pk_fma_f32 v[8:9], v[4:5], v[122:123], v[8:9]
	v_add_f32_dpp v12, v12, v12 row_half_mirror row_mask:0xf bank_mask:0xf bound_ctrl:1
	ds_read_b128 v[180:183], v84 offset:30336
	ds_read_b128 v[168:171], v84 offset:29568
	v_add_f32_dpp v12, v12, v12 row_mirror row_mask:0xf bank_mask:0xf bound_ctrl:1
	ds_read_b128 v[176:179], v84 offset:30080
	ds_read_b128 v[172:175], v84 offset:29824
	ds_read_b128 v[184:187], v84 offset:30592
	v_pk_fma_f32 v[2:3], v[124:125], v[12:13], v[6:7] op_sel_hi:[1,0,1] neg_lo:[0,1,0] neg_hi:[0,1,0]
	v_pk_fma_f32 v[4:5], v[126:127], v[12:13], v[8:9] op_sel_hi:[1,0,1] neg_lo:[0,1,0] neg_hi:[0,1,0]
	s_waitcnt lgkmcnt(5)
	v_pk_mul_f32 v[10:11], v[2:3], v[156:157]
	v_pk_fma_f32 v[10:11], v[4:5], v[158:159], v[10:11]
	v_pk_mul_f32 v[14:15], v[2:3], v[136:137]
	v_add_f32_e32 v12, v10, v11
	v_pk_fma_f32 v[14:15], v[4:5], v[138:139], v[14:15]
	v_add_f32_e32 v112, v14, v15
	v_add_f32_dpp v12, v12, v12 quad_perm:[1,0,3,2] row_mask:0xf bank_mask:0xf bound_ctrl:1
	v_pk_mul_f32 v[6:7], v[152:153], v[92:93] op_sel:[0,1] op_sel_hi:[1,1]
	v_pk_mul_f32 v[8:9], v[154:155], v[92:93] op_sel:[0,1] op_sel_hi:[1,1]
	v_add_f32_dpp v12, v12, v12 quad_perm:[2,3,0,1] row_mask:0xf bank_mask:0xf bound_ctrl:1
	v_pk_fma_f32 v[6:7], v[2:3], v[144:145], v[6:7]
	v_pk_fma_f32 v[8:9], v[4:5], v[146:147], v[8:9]
	v_add_f32_dpp v12, v12, v12 row_half_mirror row_mask:0xf bank_mask:0xf bound_ctrl:1
	ds_read_b128 v[34:37], v84 offset:31680
	ds_read_b128 v[22:25], v84 offset:30912
	v_add_f32_dpp v12, v12, v12 row_mirror row_mask:0xf bank_mask:0xf bound_ctrl:1
	ds_read_b128 v[30:33], v84 offset:31424
	ds_read_b128 v[26:29], v84 offset:31168
	ds_read_b128 v[38:41], v84 offset:31936
	v_pk_fma_f32 v[2:3], v[148:149], v[12:13], v[6:7] op_sel_hi:[1,0,1] neg_lo:[0,1,0] neg_hi:[0,1,0]
	v_pk_fma_f32 v[4:5], v[150:151], v[12:13], v[8:9] op_sel_hi:[1,0,1] neg_lo:[0,1,0] neg_hi:[0,1,0]
	s_waitcnt lgkmcnt(5)
	v_pk_mul_f32 v[10:11], v[2:3], v[180:181]
	v_pk_fma_f32 v[10:11], v[4:5], v[182:183], v[10:11]
	v_pk_mul_f32 v[14:15], v[2:3], v[160:161]
	v_add_f32_e32 v12, v10, v11
	v_pk_fma_f32 v[14:15], v[4:5], v[162:163], v[14:15]
	v_add_f32_e32 v113, v14, v15
	v_add_f32_dpp v12, v12, v12 quad_perm:[1,0,3,2] row_mask:0xf bank_mask:0xf bound_ctrl:1
	v_pk_mul_f32 v[6:7], v[176:177], v[94:95] op_sel_hi:[1,0]
	v_pk_mul_f32 v[8:9], v[178:179], v[94:95] op_sel_hi:[1,0]
	v_add_f32_dpp v12, v12, v12 quad_perm:[2,3,0,1] row_mask:0xf bank_mask:0xf bound_ctrl:1
	v_pk_fma_f32 v[6:7], v[2:3], v[168:169], v[6:7]
	v_pk_fma_f32 v[8:9], v[4:5], v[170:171], v[8:9]
	v_add_f32_dpp v12, v12, v12 row_half_mirror row_mask:0xf bank_mask:0xf bound_ctrl:1
	ds_read_b128 v[132:135], v84 offset:33024
	ds_read_b128 v[120:123], v84 offset:32256
	v_add_f32_dpp v12, v12, v12 row_mirror row_mask:0xf bank_mask:0xf bound_ctrl:1
	ds_read_b128 v[128:131], v84 offset:32768
	ds_read_b128 v[116:119], v96 offset:96
	ds_read_b128 v[124:127], v84 offset:32512
	ds_read_b128 v[136:139], v84 offset:33280
	v_pk_fma_f32 v[2:3], v[172:173], v[12:13], v[6:7] op_sel_hi:[1,0,1] neg_lo:[0,1,0] neg_hi:[0,1,0]
	v_pk_fma_f32 v[4:5], v[174:175], v[12:13], v[8:9] op_sel_hi:[1,0,1] neg_lo:[0,1,0] neg_hi:[0,1,0]
	s_waitcnt lgkmcnt(6)
; #define LAS __attribute__((address_space(3)))
; template <int CTRL> __device__ __forceinline__ float dpp_f(float v) { return __int_as_float(__builtin_amdgcn_update_dpp(0, __float_as_int(v), CTRL, 0xf, 0xf, true)); }
; __device__ __forceinline__ float row16_sum(float v) { v += dpp_f<0xB1>(v); v += dpp_f<0x4E>(v); v += dpp_f<0x141>(v); v += dpp_f<0x140>(v); return v; }
; __device__ __forceinline__ float tr16_sum(const float (&p)[16], int kq) {
;     const bool b3 = (kq & 8) != 0, b2 = (kq & 4) != 0, b1 = (kq & 2) != 0, b0 = (kq & 1) != 0;
;     float q[8], r[4], u[2];
; #pragma unroll
;     for (int t = 0; t < 8; ++t) { const float keep = b3 ? p[t + 8] : p[t], send = b3 ? p[t] : p[t + 8]; q[t] = keep + dpp_f<0x140>(send); }
; #pragma unroll
;     for (int t = 0; t < 4; ++t) { const float keep = b2 ? q[t + 4] : q[t], send = b2 ? q[t] : q[t + 4]; r[t] = keep + dpp_f<0x141>(send); }
; #pragma unroll
;     for (int t = 0; t < 2; ++t) { const float keep = b1 ? r[t + 2] : r[t], send = b1 ? r[t] : r[t + 2]; u[t] = keep + dpp_f<0x4E>(send); }
;     const float keep = b0 ? u[1] : u[0], send = b0 ? u[0] : u[1];
;     return keep + dpp_f<0xB1>(send);
; __device__ __forceinline__ void rwkv_scan_unit(LAS unsigned char* lds, const float* Wd, const float* V, const bf16_t* RKKB, float* Yraw, int p, int rg, int tid) {
;     ...
;             for (int st = 0; st < SCAN_CH; ++st) {
;                 f32x4 wn = w, bn = b, kn = k, kkn = kk, rn = r; float vn = v;
;                 if (st + 1 < SCAN_CH) { const int o = (st + 1) * SCAN_STEP_B;
;                     wn = *(LAS const f32x4*)(sl + o); bn = *(LAS const f32x4*)(sl + o + 256); kn = *(LAS const f32x4*)(sl + o + 512); kkn = *(LAS const f32x4*)(sl + o + 768); rn = *(LAS const f32x4*)(sl + o + 1024);
;                     vn = *(LAS const float*)(vl + o); }
;                 float sa = (S[0] * kk[0] + S[1] * kk[1]) + (S[2] * kk[2] + S[3] * kk[3]);
;                 const f32x4 kvt = k * v;
;                 sa = -row16_sum(sa);
;                 S = S * w + (b * sa + kvt);
;                 yp[st & 15] = (S[0] * r[0] + S[1] * r[1]) + (S[2] * r[2] + S[3] * r[3]);
;                 if ((st & 15) == 15) yo[(size_t)(st - 15) * 64] = tr16_sum(yp, kq);
;                 w = wn; b = bn; k = kn; kk = kkn; r = rn; v = vn;
;             }
	v_pk_mul_f32 v[10:11], v[2:3], v[34:35]
	v_pk_fma_f32 v[10:11], v[4:5], v[36:37], v[10:11]
	v_pk_mul_f32 v[14:15], v[2:3], v[184:185]
	v_add_f32_e32 v12, v10, v11
	v_pk_fma_f32 v[14:15], v[4:5], v[186:187], v[14:15]
	v_add_f32_e32 v114, v14, v15
	v_add_f32_dpp v12, v12, v12 quad_perm:[1,0,3,2] row_mask:0xf bank_mask:0xf bound_ctrl:1
	v_pk_mul_f32 v[6:7], v[30:31], v[94:95] op_sel:[0,1] op_sel_hi:[1,1]
	v_pk_mul_f32 v[8:9], v[32:33], v[94:95] op_sel:[0,1] op_sel_hi:[1,1]
	v_add_f32_dpp v12, v12, v12 quad_perm:[2,3,0,1] row_mask:0xf bank_mask:0xf bound_ctrl:1
	v_pk_fma_f32 v[6:7], v[2:3], v[22:23], v[6:7]
	v_pk_fma_f32 v[8:9], v[4:5], v[24:25], v[8:9]
	v_add_f32_dpp v12, v12, v12 row_half_mirror row_mask:0xf bank_mask:0xf bound_ctrl:1
	ds_read_b128 v[156:159], v84 offset:34368
	ds_read_b128 v[144:147], v84 offset:33600
	v_add_f32_dpp v12, v12, v12 row_mirror row_mask:0xf bank_mask:0xf bound_ctrl:1
	ds_read_b128 v[152:155], v84 offset:34112
	ds_read_b128 v[148:151], v84 offset:33856
	ds_read_b128 v[160:163], v84 offset:34624
	v_pk_fma_f32 v[2:3], v[26:27], v[12:13], v[6:7] op_sel_hi:[1,0,1] neg_lo:[0,1,0] neg_hi:[0,1,0]
	v_pk_fma_f32 v[4:5], v[28:29], v[12:13], v[8:9] op_sel_hi:[1,0,1] neg_lo:[0,1,0] neg_hi:[0,1,0]
	s_waitcnt lgkmcnt(5)
	v_pk_mul_f32 v[10:11], v[2:3], v[132:133]
	v_pk_fma_f32 v[10:11], v[4:5], v[134:135], v[10:11]
	v_pk_mul_f32 v[14:15], v[2:3], v[38:39]
	v_add_f32_e32 v12, v10, v11
	v_pk_fma_f32 v[14:15], v[4:5], v[40:41], v[14:15]
	v_add_f32_e32 v115, v14, v15
	v_add_f32_dpp v12, v12, v12 quad_perm:[1,0,3,2] row_mask:0xf bank_mask:0xf bound_ctrl:1
	v_pk_mul_f32 v[6:7], v[128:129], v[116:117] op_sel_hi:[1,0]
	v_pk_mul_f32 v[8:9], v[130:131], v[116:117] op_sel_hi:[1,0]
	v_add_f32_dpp v12, v12, v12 quad_perm:[2,3,0,1] row_mask:0xf bank_mask:0xf bound_ctrl:1
	v_pk_fma_f32 v[6:7], v[2:3], v[120:121], v[6:7]
	v_pk_fma_f32 v[8:9], v[4:5], v[122:123], v[8:9]
	v_add_f32_dpp v12, v12, v12 row_half_mirror row_mask:0xf bank_mask:0xf bound_ctrl:1
	ds_read_b128 v[180:183], v84 offset:35712
	ds_read_b128 v[168:171], v84 offset:34944
	v_add_f32_dpp v12, v12, v12 row_mirror row_mask:0xf bank_mask:0xf bound_ctrl:1
	ds_read_b128 v[176:179], v84 offset:35456
	ds_read_b128 v[172:175], v84 offset:35200
	ds_read_b128 v[184:187], v84 offset:35968
	v_pk_fma_f32 v[2:3], v[124:125], v[12:13], v[6:7] op_sel_hi:[1,0,1] neg_lo:[0,1,0] neg_hi:[0,1,0]
	v_pk_fma_f32 v[4:5], v[126:127], v[12:13], v[8:9] op_sel_hi:[1,0,1] neg_lo:[0,1,0] neg_hi:[0,1,0]
	s_waitcnt lgkmcnt(5)
	v_pk_mul_f32 v[10:11], v[2:3], v[156:157]
	v_pk_fma_f32 v[10:11], v[4:5], v[158:159], v[10:11]
	v_pk_mul_f32 v[14:15], v[2:3], v[136:137]
	v_add_f32_e32 v12, v10, v11
	v_pk_fma_f32 v[14:15], v[4:5], v[138:139], v[14:15]
	v_add_f32_e32 v44, v14, v15
	v_add_f32_dpp v12, v12, v12 quad_perm:[1,0,3,2] row_mask:0xf bank_mask:0xf bound_ctrl:1
	v_add_f32_dpp v108, v108, v108 row_mirror row_mask:0xf bank_mask:0x3 bound_ctrl:1
	v_add_f32_dpp v108, v44, v44 row_mirror row_mask:0xf bank_mask:0xc bound_ctrl:1
	v_add_f32_dpp v12, v12, v12 quad_perm:[2,3,0,1] row_mask:0xf bank_mask:0xf bound_ctrl:1
	v_pk_mul_f32 v[6:7], v[152:153], v[116:117] op_sel:[0,1] op_sel_hi:[1,1]
	v_pk_mul_f32 v[8:9], v[154:155], v[116:117] op_sel:[0,1] op_sel_hi:[1,1]
	v_add_f32_dpp v12, v12, v12 row_half_mirror row_mask:0xf bank_mask:0xf bound_ctrl:1
	v_pk_fma_f32 v[6:7], v[2:3], v[144:145], v[6:7]
	v_pk_fma_f32 v[8:9], v[4:5], v[146:147], v[8:9]
	v_add_f32_dpp v12, v12, v12 row_mirror row_mask:0xf bank_mask:0xf bound_ctrl:1
	ds_read_b128 v[34:37], v84 offset:37056
	ds_read_b128 v[22:25], v84 offset:36288
	ds_read_b128 v[30:33], v84 offset:36800
	ds_read_b128 v[26:29], v84 offset:36544
	ds_read_b128 v[38:41], v84 offset:37312
	v_pk_fma_f32 v[2:3], v[148:149], v[12:13], v[6:7] op_sel_hi:[1,0,1] neg_lo:[0,1,0] neg_hi:[0,1,0]
	v_pk_fma_f32 v[4:5], v[150:151], v[12:13], v[8:9] op_sel_hi:[1,0,1] neg_lo:[0,1,0] neg_hi:[0,1,0]
	s_waitcnt lgkmcnt(5)
	v_pk_mul_f32 v[10:11], v[2:3], v[180:181]
	v_pk_fma_f32 v[10:11], v[4:5], v[182:183], v[10:11]
	v_pk_mul_f32 v[14:15], v[2:3], v[160:161]
	v_add_f32_e32 v12, v10, v11
	v_pk_fma_f32 v[14:15], v[4:5], v[162:163], v[14:15]
	v_add_f32_e32 v44, v14, v15
	v_add_f32_dpp v12, v12, v12 quad_perm:[1,0,3,2] row_mask:0xf bank_mask:0xf bound_ctrl:1
	v_add_f32_dpp v109, v109, v109 row_mirror row_mask:0xf bank_mask:0x3 bound_ctrl:1
	v_add_f32_dpp v109, v44, v44 row_mirror row_mask:0xf bank_mask:0xc bound_ctrl:1
	v_add_f32_dpp v12, v12, v12 quad_perm:[2,3,0,1] row_mask:0xf bank_mask:0xf bound_ctrl:1
	v_pk_mul_f32 v[6:7], v[176:177], v[118:119] op_sel_hi:[1,0]
	v_pk_mul_f32 v[8:9], v[178:179], v[118:119] op_sel_hi:[1,0]
	v_add_f32_dpp v12, v12, v12 row_half_mirror row_mask:0xf bank_mask:0xf bound_ctrl:1
	v_pk_fma_f32 v[6:7], v[2:3], v[168:169], v[6:7]
	v_pk_fma_f32 v[8:9], v[4:5], v[170:171], v[8:9]
	v_add_f32_dpp v12, v12, v12 row_mirror row_mask:0xf bank_mask:0xf bound_ctrl:1
	ds_read_b128 v[132:135], v84 offset:38400
	ds_read_b128 v[120:123], v84 offset:37632
	ds_read_b128 v[128:131], v84 offset:38144
	ds_read_b128 v[92:95], v96 offset:112
	ds_read_b128 v[124:127], v84 offset:37888
	ds_read_b128 v[136:139], v84 offset:38656
	v_pk_fma_f32 v[2:3], v[172:173], v[12:13], v[6:7] op_sel_hi:[1,0,1] neg_lo:[0,1,0] neg_hi:[0,1,0]
	v_pk_fma_f32 v[4:5], v[174:175], v[12:13], v[8:9] op_sel_hi:[1,0,1] neg_lo:[0,1,0] neg_hi:[0,1,0]
	s_waitcnt lgkmcnt(6)
; #define LAS __attribute__((address_space(3)))
; template <int CTRL> __device__ __forceinline__ float dpp_f(float v) { return __int_as_float(__builtin_amdgcn_update_dpp(0, __float_as_int(v), CTRL, 0xf, 0xf, true)); }
; __device__ __forceinline__ float row16_sum(float v) { v += dpp_f<0xB1>(v); v += dpp_f<0x4E>(v); v += dpp_f<0x141>(v); v += dpp_f<0x140>(v); return v; }
; __device__ __forceinline__ float tr16_sum(const float (&p)[16], int kq) {
;     const bool b3 = (kq & 8) != 0, b2 = (kq & 4) != 0, b1 = (kq & 2) != 0, b0 = (kq & 1) != 0;
;     float q[8], r[4], u[2];
; #pragma unroll
;     for (int t = 0; t < 8; ++t) { const float keep = b3 ? p[t + 8] : p[t], send = b3 ? p[t] : p[t + 8]; q[t] = keep + dpp_f<0x140>(send); }
; #pragma unroll
;     for (int t = 0; t < 4; ++t) { const float keep = b2 ? q[t + 4] : q[t], send = b2 ? q[t] : q[t + 4]; r[t] = keep + dpp_f<0x141>(send); }
; #pragma unroll
;     for (int t = 0; t < 2; ++t) { const float keep = b1 ? r[t + 2] : r[t], send = b1 ? r[t] : r[t + 2]; u[t] = keep + dpp_f<0x4E>(send); }
;     const float keep = b0 ? u[1] : u[0], send = b0 ? u[0] : u[1];
;     return keep + dpp_f<0xB1>(send);
; __device__ __forceinline__ void rwkv_scan_unit(LAS unsigned char* lds, const float* Wd, const float* V, const bf16_t* RKKB, float* Yraw, int p, int rg, int tid) {
;     ...
;             for (int st = 0; st < SCAN_CH; ++st) {
;                 f32x4 wn = w, bn = b, kn = k, kkn = kk, rn = r; float vn = v;
;                 if (st + 1 < SCAN_CH) { const int o = (st + 1) * SCAN_STEP_B;
;                     wn = *(LAS const f32x4*)(sl + o); bn = *(LAS const f32x4*)(sl + o + 256); kn = *(LAS const f32x4*)(sl + o + 512); kkn = *(LAS const f32x4*)(sl + o + 768); rn = *(LAS const f32x4*)(sl + o + 1024);
;                     vn = *(LAS const float*)(vl + o); }
;                 float sa = (S[0] * kk[0] + S[1] * kk[1]) + (S[2] * kk[2] + S[3] * kk[3]);
;                 const f32x4 kvt = k * v;
;                 sa = -row16_sum(sa);
;                 S = S * w + (b * sa + kvt);
;                 yp[st & 15] = (S[0] * r[0] + S[1] * r[1]) + (S[2] * r[2] + S[3] * r[3]);
;                 if ((st & 15) == 15) yo[(size_t)(st - 15) * 64] = tr16_sum(yp, kq);
;                 w = wn; b = bn; k = kn; kk = kkn; r = rn; v = vn;
;             }
	v_pk_mul_f32 v[10:11], v[2:3], v[34:35]
	v_pk_fma_f32 v[10:11], v[4:5], v[36:37], v[10:11]
	v_pk_mul_f32 v[14:15], v[2:3], v[184:185]
	v_add_f32_e32 v12, v10, v11
	v_pk_fma_f32 v[14:15], v[4:5], v[186:187], v[14:15]
	v_add_f32_e32 v44, v14, v15
	v_add_f32_dpp v12, v12, v12 quad_perm:[1,0,3,2] row_mask:0xf bank_mask:0xf bound_ctrl:1
	v_add_f32_dpp v110, v110, v110 row_mirror row_mask:0xf bank_mask:0x3 bound_ctrl:1
	v_add_f32_dpp v110, v44, v44 row_mirror row_mask:0xf bank_mask:0xc bound_ctrl:1
	v_add_f32_dpp v12, v12, v12 quad_perm:[2,3,0,1] row_mask:0xf bank_mask:0xf bound_ctrl:1
	v_pk_mul_f32 v[6:7], v[30:31], v[118:119] op_sel:[0,1] op_sel_hi:[1,1]
	v_pk_mul_f32 v[8:9], v[32:33], v[118:119] op_sel:[0,1] op_sel_hi:[1,1]
	v_add_f32_dpp v12, v12, v12 row_half_mirror row_mask:0xf bank_mask:0xf bound_ctrl:1
	v_pk_fma_f32 v[6:7], v[2:3], v[22:23], v[6:7]
	v_pk_fma_f32 v[8:9], v[4:5], v[24:25], v[8:9]
	v_add_f32_dpp v12, v12, v12 row_mirror row_mask:0xf bank_mask:0xf bound_ctrl:1
	ds_read_b128 v[156:159], v84 offset:39744
	ds_read_b128 v[144:147], v84 offset:38976
	ds_read_b128 v[152:155], v84 offset:39488
	ds_read_b128 v[148:151], v84 offset:39232
	ds_read_b128 v[160:163], v84 offset:40000
	v_pk_fma_f32 v[2:3], v[26:27], v[12:13], v[6:7] op_sel_hi:[1,0,1] neg_lo:[0,1,0] neg_hi:[0,1,0]
	v_pk_fma_f32 v[4:5], v[28:29], v[12:13], v[8:9] op_sel_hi:[1,0,1] neg_lo:[0,1,0] neg_hi:[0,1,0]
	s_waitcnt lgkmcnt(5)
	v_pk_mul_f32 v[10:11], v[2:3], v[132:133]
	v_pk_fma_f32 v[10:11], v[4:5], v[134:135], v[10:11]
	v_pk_mul_f32 v[14:15], v[2:3], v[38:39]
	v_add_f32_e32 v12, v10, v11
	v_pk_fma_f32 v[14:15], v[4:5], v[40:41], v[14:15]
	v_add_f32_e32 v44, v14, v15
	v_add_f32_dpp v12, v12, v12 quad_perm:[1,0,3,2] row_mask:0xf bank_mask:0xf bound_ctrl:1
	v_add_f32_dpp v111, v111, v111 row_mirror row_mask:0xf bank_mask:0x3 bound_ctrl:1
	v_add_f32_dpp v111, v44, v44 row_mirror row_mask:0xf bank_mask:0xc bound_ctrl:1
	v_add_f32_dpp v12, v12, v12 quad_perm:[2,3,0,1] row_mask:0xf bank_mask:0xf bound_ctrl:1
	v_pk_mul_f32 v[6:7], v[128:129], v[92:93] op_sel_hi:[1,0]
	v_pk_mul_f32 v[8:9], v[130:131], v[92:93] op_sel_hi:[1,0]
	v_add_f32_dpp v12, v12, v12 row_half_mirror row_mask:0xf bank_mask:0xf bound_ctrl:1
	v_pk_fma_f32 v[6:7], v[2:3], v[120:121], v[6:7]
	v_pk_fma_f32 v[8:9], v[4:5], v[122:123], v[8:9]
	v_add_f32_dpp v12, v12, v12 row_mirror row_mask:0xf bank_mask:0xf bound_ctrl:1
	ds_read_b128 v[180:183], v84 offset:41088
	ds_read_b128 v[168:171], v84 offset:40320
	ds_read_b128 v[176:179], v84 offset:40832
	ds_read_b128 v[172:175], v84 offset:40576
	ds_read_b128 v[184:187], v84 offset:41344
	v_pk_fma_f32 v[2:3], v[124:125], v[12:13], v[6:7] op_sel_hi:[1,0,1] neg_lo:[0,1,0] neg_hi:[0,1,0]
	v_pk_fma_f32 v[4:5], v[126:127], v[12:13], v[8:9] op_sel_hi:[1,0,1] neg_lo:[0,1,0] neg_hi:[0,1,0]
	s_waitcnt lgkmcnt(5)
	v_pk_mul_f32 v[10:11], v[2:3], v[156:157]
	v_pk_fma_f32 v[10:11], v[4:5], v[158:159], v[10:11]
	v_pk_mul_f32 v[14:15], v[2:3], v[136:137]
	v_add_f32_e32 v12, v10, v11
	v_pk_fma_f32 v[14:15], v[4:5], v[138:139], v[14:15]
	v_add_f32_e32 v44, v14, v15
	v_add_f32_dpp v12, v12, v12 quad_perm:[1,0,3,2] row_mask:0xf bank_mask:0xf bound_ctrl:1
	v_add_f32_dpp v112, v112, v112 row_mirror row_mask:0xf bank_mask:0x3 bound_ctrl:1
	v_add_f32_dpp v112, v44, v44 row_mirror row_mask:0xf bank_mask:0xc bound_ctrl:1
	v_add_f32_dpp v12, v12, v12 quad_perm:[2,3,0,1] row_mask:0xf bank_mask:0xf bound_ctrl:1
	v_pk_mul_f32 v[6:7], v[152:153], v[92:93] op_sel:[0,1] op_sel_hi:[1,1]
	v_pk_mul_f32 v[8:9], v[154:155], v[92:93] op_sel:[0,1] op_sel_hi:[1,1]
	v_add_f32_dpp v12, v12, v12 row_half_mirror row_mask:0xf bank_mask:0xf bound_ctrl:1
	v_pk_fma_f32 v[6:7], v[2:3], v[144:145], v[6:7]
	v_pk_fma_f32 v[8:9], v[4:5], v[146:147], v[8:9]
	v_add_f32_dpp v12, v12, v12 row_mirror row_mask:0xf bank_mask:0xf bound_ctrl:1
	ds_read_b128 v[34:37], v84 offset:42432
	ds_read_b128 v[22:25], v84 offset:41664
	ds_read_b128 v[30:33], v84 offset:42176
	ds_read_b128 v[26:29], v84 offset:41920
	ds_read_b128 v[38:41], v84 offset:42688
	v_pk_fma_f32 v[2:3], v[148:149], v[12:13], v[6:7] op_sel_hi:[1,0,1] neg_lo:[0,1,0] neg_hi:[0,1,0]
	v_pk_fma_f32 v[4:5], v[150:151], v[12:13], v[8:9] op_sel_hi:[1,0,1] neg_lo:[0,1,0] neg_hi:[0,1,0]
	s_waitcnt lgkmcnt(5)
; #define LAS __attribute__((address_space(3)))
; template <int CTRL> __device__ __forceinline__ float dpp_f(float v) { return __int_as_float(__builtin_amdgcn_update_dpp(0, __float_as_int(v), CTRL, 0xf, 0xf, true)); }
; __device__ __forceinline__ float row16_sum(float v) { v += dpp_f<0xB1>(v); v += dpp_f<0x4E>(v); v += dpp_f<0x141>(v); v += dpp_f<0x140>(v); return v; }
; __device__ __forceinline__ float tr16_sum(const float (&p)[16], int kq) {
;     const bool b3 = (kq & 8) != 0, b2 = (kq & 4) != 0, b1 = (kq & 2) != 0, b0 = (kq & 1) != 0;
;     float q[8], r[4], u[2];
; #pragma unroll
;     for (int t = 0; t < 8; ++t) { const float keep = b3 ? p[t + 8] : p[t], send = b3 ? p[t] : p[t + 8]; q[t] = keep + dpp_f<0x140>(send); }
; #pragma unroll
;     for (int t = 0; t < 4; ++t) { const float keep = b2 ? q[t + 4] : q[t], send = b2 ? q[t] : q[t + 4]; r[t] = keep + dpp_f<0x141>(send); }
; #pragma unroll
;     for (int t = 0; t < 2; ++t) { const float keep = b1 ? r[t + 2] : r[t], send = b1 ? r[t] : r[t + 2]; u[t] = keep + dpp_f<0x4E>(send); }
;     const float keep = b0 ? u[1] : u[0], send = b0 ? u[0] : u[1];
;     return keep + dpp_f<0xB1>(send);
; __device__ __forceinline__ void rwkv_scan_unit(LAS unsigned char* lds, const float* Wd, const float* V, const bf16_t* RKKB, float* Yraw, int p, int rg, int tid) {
;     ...
;             for (int st = 0; st < SCAN_CH; ++st) {
;                 f32x4 wn = w, bn = b, kn = k, kkn = kk, rn = r; float vn = v;
;                 if (st + 1 < SCAN_CH) { const int o = (st + 1) * SCAN_STEP_B;
;                     wn = *(LAS const f32x4*)(sl + o); bn = *(LAS const f32x4*)(sl + o + 256); kn = *(LAS const f32x4*)(sl + o + 512); kkn = *(LAS const f32x4*)(sl + o + 768); rn = *(LAS const f32x4*)(sl + o + 1024);
;                     vn = *(LAS const float*)(vl + o); }
;                 float sa = (S[0] * kk[0] + S[1] * kk[1]) + (S[2] * kk[2] + S[3] * kk[3]);
;                 const f32x4 kvt = k * v;
;                 sa = -row16_sum(sa);
;                 S = S * w + (b * sa + kvt);
;                 yp[st & 15] = (S[0] * r[0] + S[1] * r[1]) + (S[2] * r[2] + S[3] * r[3]);
;                 if ((st & 15) == 15) yo[(size_t)(st - 15) * 64] = tr16_sum(yp, kq);
;                 w = wn; b = bn; k = kn; kk = kkn; r = rn; v = vn;
;             }
;         }
;         __syncthreads();
;     }
	v_pk_mul_f32 v[10:11], v[2:3], v[180:181]
	v_pk_fma_f32 v[10:11], v[4:5], v[182:183], v[10:11]
	v_pk_mul_f32 v[14:15], v[2:3], v[160:161]
	v_add_f32_e32 v12, v10, v11
	v_pk_fma_f32 v[14:15], v[4:5], v[162:163], v[14:15]
	v_add_f32_e32 v44, v14, v15
	v_add_f32_dpp v12, v12, v12 quad_perm:[1,0,3,2] row_mask:0xf bank_mask:0xf bound_ctrl:1
	v_add_f32_dpp v113, v113, v113 row_mirror row_mask:0xf bank_mask:0x3 bound_ctrl:1
	v_add_f32_dpp v113, v44, v44 row_mirror row_mask:0xf bank_mask:0xc bound_ctrl:1
	v_add_f32_dpp v12, v12, v12 quad_perm:[2,3,0,1] row_mask:0xf bank_mask:0xf bound_ctrl:1
	v_pk_mul_f32 v[6:7], v[176:177], v[94:95] op_sel_hi:[1,0]
	v_pk_mul_f32 v[8:9], v[178:179], v[94:95] op_sel_hi:[1,0]
	v_add_f32_dpp v12, v12, v12 row_half_mirror row_mask:0xf bank_mask:0xf bound_ctrl:1
	v_pk_fma_f32 v[6:7], v[2:3], v[168:169], v[6:7]
	v_pk_fma_f32 v[8:9], v[4:5], v[170:171], v[8:9]
	v_add_f32_dpp v12, v12, v12 row_mirror row_mask:0xf bank_mask:0xf bound_ctrl:1
	ds_read_b128 v[132:135], v86 offset:768
	ds_read_b128 v[120:123], v86
	ds_read_b128 v[128:131], v86 offset:512
	ds_read_b128 v[116:119], v97
	ds_read_b128 v[124:127], v86 offset:256
	ds_read_b128 v[136:139], v86 offset:1024
	v_pk_fma_f32 v[2:3], v[172:173], v[12:13], v[6:7] op_sel_hi:[1,0,1] neg_lo:[0,1,0] neg_hi:[0,1,0]
	v_pk_fma_f32 v[4:5], v[174:175], v[12:13], v[8:9] op_sel_hi:[1,0,1] neg_lo:[0,1,0] neg_hi:[0,1,0]
	s_waitcnt lgkmcnt(6)
	v_pk_mul_f32 v[10:11], v[2:3], v[34:35]
	v_pk_fma_f32 v[10:11], v[4:5], v[36:37], v[10:11]
	v_pk_mul_f32 v[14:15], v[2:3], v[184:185]
	v_add_f32_e32 v12, v10, v11
	v_pk_fma_f32 v[14:15], v[4:5], v[186:187], v[14:15]
	v_add_f32_e32 v44, v14, v15
	v_add_f32_dpp v12, v12, v12 quad_perm:[1,0,3,2] row_mask:0xf bank_mask:0xf bound_ctrl:1
	v_add_f32_dpp v114, v114, v114 row_mirror row_mask:0xf bank_mask:0x3 bound_ctrl:1
	v_add_f32_dpp v114, v44, v44 row_mirror row_mask:0xf bank_mask:0xc bound_ctrl:1
	v_add_f32_dpp v12, v12, v12 quad_perm:[2,3,0,1] row_mask:0xf bank_mask:0xf bound_ctrl:1
	v_pk_mul_f32 v[6:7], v[30:31], v[94:95] op_sel:[0,1] op_sel_hi:[1,1]
	v_pk_mul_f32 v[8:9], v[32:33], v[94:95] op_sel:[0,1] op_sel_hi:[1,1]
	v_add_f32_dpp v12, v12, v12 row_half_mirror row_mask:0xf bank_mask:0xf bound_ctrl:1
	v_pk_fma_f32 v[6:7], v[2:3], v[22:23], v[6:7]
	v_pk_fma_f32 v[8:9], v[4:5], v[24:25], v[8:9]
	v_add_f32_dpp v12, v12, v12 row_mirror row_mask:0xf bank_mask:0xf bound_ctrl:1
	ds_read_b128 v[156:159], v86 offset:2112
	ds_read_b128 v[144:147], v86 offset:1344
	ds_read_b128 v[152:155], v86 offset:1856
	ds_read_b128 v[148:151], v86 offset:1600
	ds_read_b128 v[160:163], v86 offset:2368
	v_pk_fma_f32 v[2:3], v[26:27], v[12:13], v[6:7] op_sel_hi:[1,0,1] neg_lo:[0,1,0] neg_hi:[0,1,0]
	v_pk_fma_f32 v[4:5], v[28:29], v[12:13], v[8:9] op_sel_hi:[1,0,1] neg_lo:[0,1,0] neg_hi:[0,1,0]
	v_pk_mul_f32 v[14:15], v[2:3], v[38:39]
	v_pk_fma_f32 v[14:15], v[4:5], v[40:41], v[14:15]
	v_add_f32_e32 v44, v14, v15
	v_add_f32_dpp v115, v115, v115 row_mirror row_mask:0xf bank_mask:0x3 bound_ctrl:1
	s_nop 0
	v_add_f32_dpp v115, v44, v44 row_mirror row_mask:0xf bank_mask:0xc bound_ctrl:1
	v_add_f32_dpp v108, v108, v108 row_half_mirror row_mask:0xf bank_mask:0x5 bound_ctrl:1
	v_add_f32_dpp v108, v112, v112 row_half_mirror row_mask:0xf bank_mask:0xa bound_ctrl:1
	v_add_f32_dpp v109, v109, v109 row_half_mirror row_mask:0xf bank_mask:0x5 bound_ctrl:1
	v_add_f32_dpp v109, v113, v113 row_half_mirror row_mask:0xf bank_mask:0xa bound_ctrl:1
	v_add_f32_dpp v110, v110, v110 row_half_mirror row_mask:0xf bank_mask:0x5 bound_ctrl:1
	v_add_f32_dpp v110, v114, v114 row_half_mirror row_mask:0xf bank_mask:0xa bound_ctrl:1
	v_add_f32_dpp v111, v111, v111 row_half_mirror row_mask:0xf bank_mask:0x5 bound_ctrl:1
	v_add_f32_dpp v111, v115, v115 row_half_mirror row_mask:0xf bank_mask:0xa bound_ctrl:1
	v_cndmask_b32_e64 v16, v110, v108, s[8:9]
	v_cndmask_b32_e64 v17, v108, v110, s[8:9]
	s_nop 1
	v_add_f32_dpp v16, v17, v16 quad_perm:[2,3,0,1] row_mask:0xf bank_mask:0xf bound_ctrl:1
	v_cndmask_b32_e64 v18, v111, v109, s[8:9]
	v_cndmask_b32_e64 v19, v109, v111, s[8:9]
	s_nop 1
	v_add_f32_dpp v18, v19, v18 quad_perm:[2,3,0,1] row_mask:0xf bank_mask:0xf bound_ctrl:1
	v_cndmask_b32_e64 v17, v18, v16, s[10:11]
	v_cndmask_b32_e64 v19, v16, v18, s[10:11]
	s_nop 1
	v_add_f32_dpp v17, v19, v17 quad_perm:[1,0,3,2] row_mask:0xf bank_mask:0xf bound_ctrl:1
	global_store_dword v[90:91], v17, off
	s_add_i32 s22, s22, 1
	s_mov_b64 s[18:19], 0x2000
	v_lshl_add_u64 v[60:61], v[60:61], 0, s[18:19]
	s_mov_b64 s[68:69], 0x2000
	s_cmpk_eq_i32 s22, 0x80
	s_barrier
	s_cbranch_scc1 .LBB0_370
	s_branch .Lscan_top
	s_nop 0
